# sparse-attention selected branch: row-uniform-mask fast path for non-diagonal blocks (one mask compare instead of 32 bit tests); bit-identical
# speedup vs baseline: 1.0172x; 1.0002x over previous
; DI int crow(int i, int h) { return (i & 3) + 8 * (i >> 2) + 4 * h; }
; DI void nsa_item(const Params& p_, const EvenBufs& eb_, int b, int g, int tt, unsigned char* smem) {
;     ...
;       const bool sb = (mysel >> j) & 1ull;
;       unsigned vb = sb ? 0xffffffffu : 0u;
;       bool masked = (__ballot(sb) != ~0ull);
;       if (j == (t0 >> 6)) {
;         masked = true; vb = 0;
; #pragma unroll
;         for (int mt = 0; mt < 2; ++mt)
; #pragma unroll
;           for (int i = 0; i < 16; ++i) vb |= (unsigned)(sb && (j * 64 + mt * 32 + crow(i, h) <= t)) << (mt * 16 + i);
;       }
;       if (!masked) vb = 0xffffffffu;
.LBB0_1078:
	v_bfe_i32 v128, v128, 0, 1
	s_branch .Lsel_fast

; DI float shx32(float v) { return __shfl_xor(v, 32); }
; template <bool MASKED>
; DI float online_softmax_t(f32x16 (&Sx)[2], unsigned vb, float& m, float& l) {
;   float mx = NEG;
; #pragma unroll
;   for (int mt = 0; mt < 2; ++mt)
; #pragma unroll
;     for (int i = 0; i < 16; ++i) {
;       float s = Sx[mt][i];
;       if (MASKED) { s = ((vb >> (mt * 16 + i)) & 1u) ? s : NEG; Sx[mt][i] = s; }
;       mx = fmaxf(mx, s);
;     }
;   mx = fmaxf(mx, shx32(mx));
;   const float mn = fmaxf(m, mx);
;   const float alpha = __builtin_amdgcn_exp2f((m - mn) * L2E);
;   const float mb = mn * L2E;
;   f32x2 sum2 = {0.f, 0.f};
;   const f32x2 l2e2 = {L2E, L2E}, mb2 = {mb, mb};
; #pragma unroll
;   for (int mt = 0; mt < 2; ++mt)
; #pragma unroll
;     for (int i = 0; i < 16; i += 2) {
;       const f32x2 t = (f32x2){Sx[mt][i], Sx[mt][i + 1]} * l2e2 - mb2;
;       f32x2 p = {__builtin_amdgcn_exp2f(t.x), __builtin_amdgcn_exp2f(t.y)};
;       if (MASKED) { p.x = ((vb >> (mt * 16 + i)) & 1u) ? p.x : 0.f; p.y = ((vb >> (mt * 16 + i + 1)) & 1u) ? p.y : 0.f; }
;       Sx[mt][i] = p.x; Sx[mt][i + 1] = p.y;
;       sum2 += p;
;     }
;   l = l * alpha + (sum2.x + sum2.y);
;   m = mn;
;   return alpha;
; }
.Lsel_fast:
	s_nop 3
	v_cndmask_b32_e64 v128, -1, v128, s[4:5]
	v_and_b32_e32 v129, 1, v128
	v_cmp_eq_u32_e64 s[64:65], 0, v129
	s_cmp_gt_i32 s33, -1
	s_nop 0
	v_cndmask_b32_e64 v150, v82, v214, s[64:65]
	s_nop 1
	v_cndmask_b32_e64 v151, v83, v214, s[64:65]
	v_max3_f32 v82, v150, s92, v151
	v_cndmask_b32_e64 v152, v84, v214, s[64:65]
	v_cndmask_b32_e64 v153, v85, v214, s[64:65]
	v_max3_f32 v82, v82, v152, v153
	v_cndmask_b32_e64 v154, v86, v214, s[64:65]
	v_cndmask_b32_e64 v155, v87, v214, s[64:65]
	v_max3_f32 v82, v82, v154, v155
	v_cndmask_b32_e64 v156, v88, v214, s[64:65]
	v_cndmask_b32_e64 v157, v89, v214, s[64:65]
	v_max3_f32 v82, v82, v156, v157
	v_cndmask_b32_e64 v158, v90, v214, s[64:65]
	v_cndmask_b32_e64 v159, v91, v214, s[64:65]
	v_max3_f32 v82, v82, v158, v159
	v_cndmask_b32_e64 v160, v92, v214, s[64:65]
	v_cndmask_b32_e64 v161, v93, v214, s[64:65]
	v_max3_f32 v82, v82, v160, v161
	v_cndmask_b32_e64 v174, v94, v214, s[64:65]
	v_cndmask_b32_e64 v175, v95, v214, s[64:65]
	v_max3_f32 v82, v82, v174, v175
	v_cndmask_b32_e64 v176, v96, v214, s[64:65]
	v_cndmask_b32_e64 v177, v97, v214, s[64:65]
	v_max3_f32 v84, v82, v176, v177
	s_nop 1
	v_cndmask_b32_e64 v82, v66, v214, s[64:65]
	s_nop 1
	v_cndmask_b32_e64 v83, v67, v214, s[64:65]
	v_max3_f32 v66, v84, v82, v83
	v_cndmask_b32_e64 v84, v68, v214, s[64:65]
	v_cndmask_b32_e64 v85, v69, v214, s[64:65]
	v_max3_f32 v66, v66, v84, v85
	v_cndmask_b32_e64 v88, v70, v214, s[64:65]
	v_cndmask_b32_e64 v89, v71, v214, s[64:65]
	v_max3_f32 v66, v66, v88, v89
	v_cndmask_b32_e64 v92, v72, v214, s[64:65]
	v_cndmask_b32_e64 v93, v73, v214, s[64:65]
	v_max3_f32 v66, v66, v92, v93
	v_cndmask_b32_e64 v72, v74, v214, s[64:65]
	v_cndmask_b32_e64 v73, v75, v214, s[64:65]
	v_max3_f32 v66, v66, v72, v73
	v_cndmask_b32_e64 v74, v76, v214, s[64:65]
	v_cndmask_b32_e64 v75, v77, v214, s[64:65]
	v_max3_f32 v66, v66, v74, v75
	v_cndmask_b32_e64 v76, v78, v214, s[64:65]
	v_cndmask_b32_e64 v77, v79, v214, s[64:65]
	v_max3_f32 v66, v66, v76, v77
	v_cndmask_b32_e64 v79, v81, v214, s[64:65]
	v_cndmask_b32_e64 v78, v80, v214, s[64:65]
	v_max3_f32 v66, v66, v78, v79
	ds_bpermute_b32 v67, v169, v66
	s_waitcnt lgkmcnt(0)
	v_max3_f32 v129, v148, v66, v67
	v_mul_f32_e32 v128, 0x3fb8aa3b, v129
	v_pk_fma_f32 v[68:69], v[152:153], s[96:97], v[128:129] op_sel_hi:[1,0,0] neg_lo:[0,0,1] neg_hi:[0,0,1]
	v_pk_fma_f32 v[66:67], v[150:151], s[96:97], v[128:129] op_sel_hi:[1,0,0] neg_lo:[0,0,1] neg_hi:[0,0,1]
	v_exp_f32_e32 v68, v68
	v_exp_f32_e32 v69, v69
	v_exp_f32_e32 v66, v66
	v_exp_f32_e32 v67, v67
	v_cndmask_b32_e64 v90, v68, 0, s[64:65]
	v_cndmask_b32_e64 v91, v69, 0, s[64:65]
	v_pk_fma_f32 v[68:69], v[154:155], s[96:97], v[128:129] op_sel_hi:[1,0,0] neg_lo:[0,0,1] neg_hi:[0,0,1]
	v_cndmask_b32_e64 v86, v66, 0, s[64:65]
	v_exp_f32_e32 v68, v68
	v_exp_f32_e32 v69, v69
	v_cndmask_b32_e64 v87, v67, 0, s[64:65]
	v_pk_add_f32 v[66:67], v[86:87], 0 op_sel_hi:[1,0]
	v_cndmask_b32_e64 v94, v68, 0, s[64:65]
	v_cndmask_b32_e64 v95, v69, 0, s[64:65]
	v_pk_fma_f32 v[68:69], v[156:157], s[96:97], v[128:129] op_sel_hi:[1,0,0] neg_lo:[0,0,1] neg_hi:[0,0,1]
	v_pk_add_f32 v[66:67], v[90:91], v[66:67]
	v_exp_f32_e32 v68, v68
	v_exp_f32_e32 v69, v69
	v_pk_add_f32 v[66:67], v[94:95], v[66:67]
	v_pk_fma_f32 v[82:83], v[82:83], s[96:97], v[128:129] op_sel_hi:[1,0,0] neg_lo:[0,0,1] neg_hi:[0,0,1]
	v_cndmask_b32_e64 v96, v68, 0, s[64:65]
	v_cndmask_b32_e64 v97, v69, 0, s[64:65]
	v_pk_add_f32 v[68:69], v[96:97], v[66:67]
	v_pk_fma_f32 v[66:67], v[158:159], s[96:97], v[128:129] op_sel_hi:[1,0,0] neg_lo:[0,0,1] neg_hi:[0,0,1]
	v_exp_f32_e32 v82, v82
	v_exp_f32_e32 v66, v66
	v_exp_f32_e32 v67, v67
	v_exp_f32_e32 v83, v83
	v_pk_fma_f32 v[84:85], v[84:85], s[96:97], v[128:129] op_sel_hi:[1,0,0] neg_lo:[0,0,1] neg_hi:[0,0,1]
	v_cndmask_b32_e64 v66, v66, 0, s[64:65]
	v_cndmask_b32_e64 v67, v67, 0, s[64:65]
	v_pk_add_f32 v[70:71], v[66:67], v[68:69]
	v_pk_fma_f32 v[68:69], v[160:161], s[96:97], v[128:129] op_sel_hi:[1,0,0] neg_lo:[0,0,1] neg_hi:[0,0,1]
	v_exp_f32_e32 v84, v84
	v_exp_f32_e32 v68, v68
	v_exp_f32_e32 v69, v69
	v_exp_f32_e32 v85, v85
	v_pk_fma_f32 v[88:89], v[88:89], s[96:97], v[128:129] op_sel_hi:[1,0,0] neg_lo:[0,0,1] neg_hi:[0,0,1]
	v_cndmask_b32_e64 v68, v68, 0, s[64:65]
	v_cndmask_b32_e64 v69, v69, 0, s[64:65]
	v_pk_add_f32 v[80:81], v[68:69], v[70:71]
	v_pk_fma_f32 v[70:71], v[174:175], s[96:97], v[128:129] op_sel_hi:[1,0,0] neg_lo:[0,0,1] neg_hi:[0,0,1]
	v_exp_f32_e32 v88, v88
	v_exp_f32_e32 v70, v70
	v_exp_f32_e32 v71, v71
	v_exp_f32_e32 v89, v89
	v_pk_fma_f32 v[92:93], v[92:93], s[96:97], v[128:129] op_sel_hi:[1,0,0] neg_lo:[0,0,1] neg_hi:[0,0,1]
	v_cndmask_b32_e64 v70, v70, 0, s[64:65]
	v_cndmask_b32_e64 v71, v71, 0, s[64:65]
	v_pk_add_f32 v[150:151], v[70:71], v[80:81]
	v_pk_fma_f32 v[80:81], v[176:177], s[96:97], v[128:129] op_sel_hi:[1,0,0] neg_lo:[0,0,1] neg_hi:[0,0,1]
; DI unsigned pack2(float a, float b) { bf2_t v = __builtin_convertvector((f32x2){a, b}, bf2_t); return __builtin_bit_cast(unsigned, v); }
; #define MFMA(a, b, c) __builtin_amdgcn_mfma_f32_32x32x16_bf16((a), (b), (c), 0, 0, 0)
; DI float shx32(float v) { return __shfl_xor(v, 32); }
; template <int NDT> DI void pv_tile(const bf16_t* sV, const f32x16 (&P)[2], f32x16 (&O)[NDT], int r, int h) {
; #pragma unroll
;   for (int mt = 0; mt < 2; ++mt)
; #pragma unroll
;     for (int sp = 0; sp < 2; ++sp) {
;       u32x4 pk;
;       pk.x = pack2(P[mt][8 * sp + 0], P[mt][8 * sp + 1]); pk.y = pack2(P[mt][8 * sp + 2], P[mt][8 * sp + 3]);
;       pk.z = pack2(P[mt][8 * sp + 4], P[mt][8 * sp + 5]); pk.w = pack2(P[mt][8 * sp + 6], P[mt][8 * sp + 7]);
;       const bf16x8 pb = __builtin_bit_cast(bf16x8, pk);
; #pragma unroll
;       for (int dt = 0; dt < NDT; ++dt) {
;         const bf16_t* vp = sV + (dt * 32 + r) * 68 + mt * 32 + sp * 16 + 4 * h;
;         const bf16x4 lo = *(const bf16x4*)vp, hi = *(const bf16x4*)(vp + 8);
;         const bf16x8 va = __builtin_shufflevector(lo, hi, 0, 1, 2, 3, 4, 5, 6, 7);
;         O[dt] = MFMA(va, pb, O[dt]);
;       }
;       if (NDT > 2) __builtin_amdgcn_sched_barrier(0);
;     }
; }
; template <bool MASKED>
; DI float online_softmax_t(f32x16 (&Sx)[2], unsigned vb, float& m, float& l) {
;     ...
;   mx = fmaxf(mx, shx32(mx));
;   const float mn = fmaxf(m, mx);
;   const float alpha = __builtin_amdgcn_exp2f((m - mn) * L2E);
;   const float mb = mn * L2E;
;   f32x2 sum2 = {0.f, 0.f};
;   const f32x2 l2e2 = {L2E, L2E}, mb2 = {mb, mb};
; #pragma unroll
;   for (int mt = 0; mt < 2; ++mt)
; #pragma unroll
;     for (int i = 0; i < 16; i += 2) {
;       const f32x2 t = (f32x2){Sx[mt][i], Sx[mt][i + 1]} * l2e2 - mb2;
;       f32x2 p = {__builtin_amdgcn_exp2f(t.x), __builtin_amdgcn_exp2f(t.y)};
;       if (MASKED) { p.x = ((vb >> (mt * 16 + i)) & 1u) ? p.x : 0.f; p.y = ((vb >> (mt * 16 + i + 1)) & 1u) ? p.y : 0.f; }
;       Sx[mt][i] = p.x; Sx[mt][i + 1] = p.y;
;       sum2 += p;
;     }
;   l = l * alpha + (sum2.x + sum2.y);
;   m = mn;
;   return alpha;
; }
	v_exp_f32_e32 v92, v92
	v_exp_f32_e32 v80, v80
	v_exp_f32_e32 v81, v81
	v_exp_f32_e32 v93, v93
	v_pk_fma_f32 v[72:73], v[72:73], s[96:97], v[128:129] op_sel_hi:[1,0,0] neg_lo:[0,0,1] neg_hi:[0,0,1]
	v_cndmask_b32_e64 v80, v80, 0, s[64:65]
	v_cndmask_b32_e64 v81, v81, 0, s[64:65]
	v_pk_add_f32 v[150:151], v[80:81], v[150:151]
	v_cndmask_b32_e64 v82, v82, 0, s[64:65]
	v_cndmask_b32_e64 v83, v83, 0, s[64:65]
	v_exp_f32_e32 v72, v72
	v_exp_f32_e32 v73, v73
	v_pk_fma_f32 v[74:75], v[74:75], s[96:97], v[128:129] op_sel_hi:[1,0,0] neg_lo:[0,0,1] neg_hi:[0,0,1]
	v_pk_add_f32 v[150:151], v[82:83], v[150:151]
	v_cndmask_b32_e64 v84, v84, 0, s[64:65]
	v_cndmask_b32_e64 v85, v85, 0, s[64:65]
	v_exp_f32_e32 v74, v74
	v_exp_f32_e32 v75, v75
	v_pk_fma_f32 v[76:77], v[76:77], s[96:97], v[128:129] op_sel_hi:[1,0,0] neg_lo:[0,0,1] neg_hi:[0,0,1]
	v_pk_add_f32 v[150:151], v[84:85], v[150:151]
	v_cndmask_b32_e64 v88, v88, 0, s[64:65]
	v_cndmask_b32_e64 v89, v89, 0, s[64:65]
	v_exp_f32_e32 v76, v76
	v_exp_f32_e32 v77, v77
	v_pk_fma_f32 v[78:79], v[78:79], s[96:97], v[128:129] op_sel_hi:[1,0,0] neg_lo:[0,0,1] neg_hi:[0,0,1]
	v_pk_add_f32 v[150:151], v[88:89], v[150:151]
	v_cndmask_b32_e64 v92, v92, 0, s[64:65]
	v_cndmask_b32_e64 v93, v93, 0, s[64:65]
	v_exp_f32_e32 v78, v78
	v_exp_f32_e32 v79, v79
	v_pk_add_f32 v[150:151], v[92:93], v[150:151]
	v_cndmask_b32_e64 v72, v72, 0, s[64:65]
	v_cndmask_b32_e64 v73, v73, 0, s[64:65]
	v_pk_add_f32 v[150:151], v[72:73], v[150:151]
	v_cndmask_b32_e64 v74, v74, 0, s[64:65]
	v_cndmask_b32_e64 v75, v75, 0, s[64:65]
	v_pk_add_f32 v[150:151], v[74:75], v[150:151]
	v_cndmask_b32_e64 v76, v76, 0, s[64:65]
	v_cndmask_b32_e64 v77, v77, 0, s[64:65]
	v_sub_f32_e32 v128, v148, v129
	v_pk_add_f32 v[150:151], v[76:77], v[150:151]
	v_cndmask_b32_e64 v78, v78, 0, s[64:65]
	v_cndmask_b32_e64 v79, v79, 0, s[64:65]
	v_mul_f32_e32 v128, 0x3fb8aa3b, v128
	v_pk_add_f32 v[150:151], v[78:79], v[150:151]
	v_exp_f32_e32 v128, v128
	v_add_f32_e32 v184, v150, v151
	v_cvt_pk_bf16_f32 v150, v94, v95
	v_cvt_pk_bf16_f32 v151, v96, v97
	ds_read2_b64 v[94:97], v182 offset0:128 offset1:130
	ds_read2_b64 v[152:155], v182 offset0:132 offset1:134
	v_pk_mul_f32 v[50:51], v[50:51], v[128:129] op_sel_hi:[1,0]
	v_pk_mul_f32 v[52:53], v[52:53], v[128:129] op_sel_hi:[1,0]
	v_pk_mul_f32 v[54:55], v[54:55], v[128:129] op_sel_hi:[1,0]
	v_pk_mul_f32 v[56:57], v[56:57], v[128:129] op_sel_hi:[1,0]
	v_pk_mul_f32 v[58:59], v[58:59], v[128:129] op_sel_hi:[1,0]
	v_pk_mul_f32 v[60:61], v[60:61], v[128:129] op_sel_hi:[1,0]
	v_pk_mul_f32 v[62:63], v[62:63], v[128:129] op_sel_hi:[1,0]
	v_pk_mul_f32 v[64:65], v[64:65], v[128:129] op_sel_hi:[1,0]
	v_cvt_pk_bf16_f32 v148, v86, v87
	v_cvt_pk_bf16_f32 v149, v90, v91
	v_pk_mul_f32 v[34:35], v[34:35], v[128:129] op_sel_hi:[1,0]
	v_pk_mul_f32 v[36:37], v[36:37], v[128:129] op_sel_hi:[1,0]
	s_waitcnt lgkmcnt(1)
	v_mfma_f32_32x32x16_bf16 v[50:65], v[94:97], v[148:151], v[50:65]
	ds_read2_b64 v[94:97], v183 offset0:160 offset1:162
	v_mul_f32_e64 v38, v38, v128
	v_mul_f32_e64 v39, v39, v128
	v_mul_f32_e64 v40, v40, v128
	v_mul_f32_e64 v41, v41, v128
	v_pk_mul_f32 v[42:43], v[42:43], v[128:129] op_sel_hi:[1,0]
	v_pk_mul_f32 v[44:45], v[44:45], v[128:129] op_sel_hi:[1,0]
	v_pk_mul_f32 v[46:47], v[46:47], v[128:129] op_sel_hi:[1,0]
	v_pk_mul_f32 v[48:49], v[48:49], v[128:129] op_sel_hi:[1,0]
	v_cvt_pk_bf16_f32 v66, v66, v67
	v_cvt_pk_bf16_f32 v67, v68, v69
	s_waitcnt lgkmcnt(0)
	v_mfma_f32_32x32x16_bf16 v[34:49], v[94:97], v[148:151], v[34:49]
	ds_read2_b64 v[94:97], v183 offset0:164 offset1:166
	v_cvt_pk_bf16_f32 v68, v70, v71
	v_cvt_pk_bf16_f32 v69, v80, v81
	v_fmac_f32_e32 v184, v147, v128
	s_nop 0
	v_mfma_f32_32x32x16_bf16 v[50:65], v[152:155], v[66:69], v[50:65]
	s_waitcnt lgkmcnt(0)
	v_mfma_f32_32x32x16_bf16 v[34:49], v[94:97], v[66:69], v[34:49]
	v_cvt_pk_bf16_f32 v66, v82, v83
	ds_read2_b64 v[80:83], v182 offset0:136 offset1:138
	v_cvt_pk_bf16_f32 v67, v84, v85
	v_cvt_pk_bf16_f32 v68, v88, v89
	v_cvt_pk_bf16_f32 v69, v92, v93
	s_waitcnt lgkmcnt(0)
	s_nop 0
	v_mfma_f32_32x32x16_bf16 v[50:65], v[80:83], v[66:69], v[50:65]
	ds_read2_b64 v[80:83], v183 offset0:168 offset1:170
	s_waitcnt lgkmcnt(0)
	v_mfma_f32_32x32x16_bf16 v[34:49], v[80:83], v[66:69], v[34:49]
	v_cvt_pk_bf16_f32 v66, v72, v73
	ds_read2_b64 v[70:73], v182 offset0:140 offset1:142
	v_cvt_pk_bf16_f32 v67, v74, v75
	v_cvt_pk_bf16_f32 v68, v76, v77
	v_cvt_pk_bf16_f32 v69, v78, v79
	s_waitcnt lgkmcnt(0)
	s_nop 0
	v_mfma_f32_32x32x16_bf16 v[50:65], v[70:73], v[66:69], v[50:65]
	ds_read2_b64 v[70:73], v183 offset0:172 offset1:174
	s_waitcnt lgkmcnt(0)
	v_mfma_f32_32x32x16_bf16 v[34:49], v[70:73], v[66:69], v[34:49]
	s_cbranch_scc0 .LBB0_1081
	v_mov_b32_e32 v147, v184
	v_mov_b32_e32 v148, v129
	s_mov_b64 s[4:5], s[68:69]
	s_mov_b32 s6, s33
	s_branch .LBB0_1073
